# grid barrier: non-leader workgroups wait on the top-level generation word directly (one hop less), per-XCD generation word no longer updated
# speedup vs baseline: 1.0118x; 1.0118x over previous
.LBB0_209:
	s_or_b64 exec, exec, s[8:9]
	v_cvt_f32_u32_e32 v4, v2
	s_waitcnt vmcnt(0)
	v_readfirstlane_b32 s6, v3
	v_sub_u32_e32 v3, 0, v2
	v_rcp_iflag_f32_e32 v4, v4
	v_add_u32_e32 v5, s6, v1
	v_mul_f32_e32 v4, 0x4f7ffffe, v4
	v_cvt_u32_f32_e32 v4, v4
	v_mul_lo_u32 v1, v3, v4
	v_mul_hi_u32 v1, v4, v1
	v_add_u32_e32 v1, v4, v1
	v_mul_hi_u32 v1, v5, v1
	v_mul_lo_u32 v3, v1, v2
	v_sub_u32_e32 v3, v5, v3
	v_add_u32_e32 v4, 1, v1
	v_cmp_ge_u32_e32 vcc, v3, v2
	s_nop 1
	v_cndmask_b32_e32 v1, v1, v4, vcc
	v_sub_u32_e32 v4, v3, v2
	v_cndmask_b32_e32 v3, v3, v4, vcc
	v_add_u32_e32 v4, 1, v1
	v_cmp_ge_u32_e32 vcc, v3, v2
	v_add_u32_e32 v3, 1, v5
	s_nop 0
	v_cndmask_b32_e32 v1, v1, v4, vcc
	v_mul_lo_u32 v4, v2, v1
	v_add_u32_e32 v2, v4, v2
	v_cmp_ne_u32_e32 vcc, v3, v2
	s_and_saveexec_b64 s[6:7], vcc
	s_xor_b64 s[6:7], exec, s[6:7]
	s_cbranch_execz .LBB0_223
	s_waitcnt lgkmcnt(0)
	v_mov_b32_e32 v0, 0
	s_add_u32 s12, s22, 0x194d0500
	s_addc_u32 s13, s23, 0
	global_load_dword v0, v0, s[12:13] sc1
	s_waitcnt vmcnt(0)
	v_cmp_eq_u32_e32 vcc, v0, v1
	s_and_saveexec_b64 s[8:9], vcc
	s_cbranch_execz .LBB0_222
	s_add_u32 s10, s22, 0x194cd200
	s_addc_u32 s11, s23, 0
	s_mov_b32 s28, 1
	s_mov_b64 s[14:15], 0
	v_mov_b32_e32 v0, 0
	s_branch .LBB0_213

.LBB0_240:
	s_or_b64 exec, exec, s[6:7]
	s_mov_b64 s[6:7], exec
	v_mbcnt_lo_u32_b32 v0, s6, 0
	v_mbcnt_hi_u32_b32 v0, s7, v0
	v_cmp_eq_u32_e32 vcc, 0, v0
	s_waitcnt vmcnt(0)
	buffer_inv sc1
	s_and_saveexec_b64 s[8:9], vcc
	s_cbranch_execz .LBB0_242
	s_bcnt1_i32_b64 s6, s[6:7]
	v_mov_b32_e32 v0, 0x2000
	v_mov_b32_e32 v1, s6
	s_nop 0

.LBB0_682:
	s_or_b64 exec, exec, s[10:11]
	v_cvt_f32_u32_e32 v4, v2
	s_waitcnt vmcnt(0)
	v_readfirstlane_b32 s8, v3
	v_sub_u32_e32 v3, 0, v2
	v_rcp_iflag_f32_e32 v4, v4
	v_add_u32_e32 v5, s8, v1
	v_mul_f32_e32 v4, 0x4f7ffffe, v4
	v_cvt_u32_f32_e32 v4, v4
	v_mul_lo_u32 v1, v3, v4
	v_mul_hi_u32 v1, v4, v1
	v_add_u32_e32 v1, v4, v1
	v_mul_hi_u32 v1, v5, v1
	v_mul_lo_u32 v3, v1, v2
	v_sub_u32_e32 v3, v5, v3
	v_add_u32_e32 v4, 1, v1
	v_cmp_ge_u32_e32 vcc, v3, v2
	s_nop 1
	v_cndmask_b32_e32 v1, v1, v4, vcc
	v_sub_u32_e32 v4, v3, v2
	v_cndmask_b32_e32 v3, v3, v4, vcc
	v_add_u32_e32 v4, 1, v1
	v_cmp_ge_u32_e32 vcc, v3, v2
	v_add_u32_e32 v3, 1, v5
	s_nop 0
	v_cndmask_b32_e32 v1, v1, v4, vcc
	v_mul_lo_u32 v4, v2, v1
	v_add_u32_e32 v2, v4, v2
	v_cmp_ne_u32_e32 vcc, v3, v2
	s_and_saveexec_b64 s[8:9], vcc
	s_xor_b64 s[8:9], exec, s[8:9]
	s_cbranch_execz .LBB0_696
	s_waitcnt lgkmcnt(0)
	v_mov_b32_e32 v0, 0
	s_add_u32 s14, s22, 0x194d0500
	s_addc_u32 s15, s23, 0
	global_load_dword v0, v0, s[14:15] sc1
	s_waitcnt vmcnt(0)
	v_cmp_eq_u32_e32 vcc, v0, v1
	s_and_saveexec_b64 s[10:11], vcc
	s_cbranch_execz .LBB0_695
	s_add_u32 s12, s22, 0x194cd200
	s_addc_u32 s13, s23, 0
	s_mov_b32 s30, 1
	s_mov_b64 s[16:17], 0
	v_mov_b32_e32 v0, 0
	s_branch .LBB0_686

.LBB0_713:
	s_or_b64 exec, exec, s[8:9]
	s_mov_b64 s[8:9], exec
	v_mbcnt_lo_u32_b32 v0, s8, 0
	v_mbcnt_hi_u32_b32 v0, s9, v0
	v_cmp_eq_u32_e32 vcc, 0, v0
	s_waitcnt vmcnt(0)
	buffer_inv sc1
	s_and_saveexec_b64 s[10:11], vcc
	s_cbranch_execz .LBB0_715
	s_bcnt1_i32_b64 s8, s[8:9]
	v_mov_b32_e32 v0, 0x2000
	v_mov_b32_e32 v1, s8
	s_nop 0

.LBB0_1291:
	s_or_b64 exec, exec, s[10:11]
	v_cvt_f32_u32_e32 v4, v2
	s_waitcnt vmcnt(0)
	v_readfirstlane_b32 s8, v3
	v_sub_u32_e32 v3, 0, v2
	v_rcp_iflag_f32_e32 v4, v4
	v_add_u32_e32 v5, s8, v1
	v_mul_f32_e32 v4, 0x4f7ffffe, v4
	v_cvt_u32_f32_e32 v4, v4
	v_mul_lo_u32 v1, v3, v4
	v_mul_hi_u32 v1, v4, v1
	v_add_u32_e32 v1, v4, v1
	v_mul_hi_u32 v1, v5, v1
	v_mul_lo_u32 v3, v1, v2
	v_sub_u32_e32 v3, v5, v3
	v_add_u32_e32 v4, 1, v1
	v_cmp_ge_u32_e32 vcc, v3, v2
	s_nop 1
	v_cndmask_b32_e32 v1, v1, v4, vcc
	v_sub_u32_e32 v4, v3, v2
	v_cndmask_b32_e32 v3, v3, v4, vcc
	v_add_u32_e32 v4, 1, v1
	v_cmp_ge_u32_e32 vcc, v3, v2
	v_add_u32_e32 v3, 1, v5
	s_nop 0
	v_cndmask_b32_e32 v1, v1, v4, vcc
	v_mul_lo_u32 v4, v2, v1
	v_add_u32_e32 v2, v4, v2
	v_cmp_ne_u32_e32 vcc, v3, v2
	s_and_saveexec_b64 s[8:9], vcc
	s_xor_b64 s[8:9], exec, s[8:9]
	s_cbranch_execz .LBB0_1305
	s_waitcnt lgkmcnt(0)
	v_mov_b32_e32 v0, 0
	s_add_u32 s14, s22, 0x194d0500
	s_addc_u32 s15, s23, 0
	global_load_dword v0, v0, s[14:15] sc1
	s_waitcnt vmcnt(0)
	v_cmp_eq_u32_e32 vcc, v0, v1
	s_and_saveexec_b64 s[10:11], vcc
	s_cbranch_execz .LBB0_1304
	s_add_u32 s12, s22, 0x194cd200
	s_mov_b32 s34, s30
	s_addc_u32 s13, s23, 0
	s_mov_b32 s30, 1
	s_mov_b64 s[16:17], 0
	v_mov_b32_e32 v0, 0
	s_branch .LBB0_1295
